# baseline (speedup 1.0000x reference)
.LBB0_154:
	s_and_b64 vcc, exec, s[2:3]
	s_cbranch_vccz .LBB0_341
	s_cmp_lt_i32 s99, 14
	s_mov_b64 s[34:35], -1
	s_cbranch_scc0 .LBB0_341
	v_mbcnt_lo_u32_b32 v1, -1, 0
	v_mbcnt_hi_u32_b32 v1, -1, v1
	s_waitcnt lgkmcnt(0)
	s_load_dwordx8 s[4:11], s[76:77], 0x90
	v_and_b32_e32 v2, 63, v1
	v_lshlrev_b32_e32 v3, 2, v2
	s_waitcnt lgkmcnt(0)
	global_load_dword v4, v3, s[4:5]
	global_load_dword v5, v3, s[6:7]
	global_load_dword v6, v3, s[8:9]
	global_load_dword v7, v3, s[10:11]
	v_and_b32_e32 v3, 64, v209
	v_xor_b32_e32 v8, 1, v209
	v_add_u32_e32 v14, 64, v3
	v_cmp_lt_i32_e32 vcc, v8, v14
	v_xor_b32_e32 v9, 2, v209
	v_xor_b32_e32 v10, 4, v209
	v_cndmask_b32_e32 v8, v209, v8, vcc
	v_lshlrev_b32_e32 v131, 2, v8
	v_cmp_lt_i32_e32 vcc, v9, v14
	v_xor_b32_e32 v11, 8, v209
	v_xor_b32_e32 v12, 16, v209
	v_cndmask_b32_e32 v9, v209, v9, vcc
	v_lshlrev_b32_e32 v141, 2, v9
	v_cmp_lt_i32_e32 vcc, v10, v14
	v_xor_b32_e32 v13, 32, v209
	v_readlane_b32 s4, v254, 39
	s_waitcnt vmcnt(0)
	v_mul_f32_e32 v8, v4, v5
	ds_bpermute_b32 v8, v131, v8
	s_waitcnt vmcnt(0)
	v_mul_f32_e32 v15, v6, v7
	ds_bpermute_b32 v15, v131, v15
	v_add_u32_e32 v3, s4, v1
	v_readlane_b32 s4, v254, 5
	s_waitcnt lgkmcnt(1)
	v_fmac_f32_e32 v8, v4, v5
	ds_bpermute_b32 v4, v141, v8
	s_waitcnt lgkmcnt(1)
	v_fmac_f32_e32 v15, v6, v7
	ds_bpermute_b32 v5, v141, v15
	v_cndmask_b32_e32 v6, v209, v10, vcc
	v_lshlrev_b32_e32 v143, 2, v6
	s_waitcnt lgkmcnt(1)
	v_add_f32_e32 v4, v8, v4
	ds_bpermute_b32 v6, v143, v4
	s_waitcnt lgkmcnt(1)
	v_add_f32_e32 v5, v15, v5
	ds_bpermute_b32 v7, v143, v5
	v_cmp_lt_i32_e32 vcc, v11, v14
	v_readlane_b32 s5, v254, 6
	s_waitcnt lgkmcnt(1)
	v_add_f32_e32 v4, v4, v6
	v_cndmask_b32_e32 v8, v209, v11, vcc
	v_lshlrev_b32_e32 v145, 2, v8
	s_waitcnt lgkmcnt(0)
	v_add_f32_e32 v5, v5, v7
	ds_bpermute_b32 v6, v145, v4
	ds_bpermute_b32 v7, v145, v5
	v_cmp_lt_i32_e32 vcc, v12, v14
	v_readfirstlane_b32 s6, v3
	s_waitcnt lgkmcnt(1)
	v_add_f32_e32 v4, v4, v6
	v_cndmask_b32_e32 v8, v209, v12, vcc
	v_lshlrev_b32_e32 v147, 2, v8
	s_waitcnt lgkmcnt(0)
	v_add_f32_e32 v5, v5, v7
	ds_bpermute_b32 v6, v147, v4
	ds_bpermute_b32 v7, v147, v5
	v_cmp_lt_i32_e32 vcc, v13, v14
	s_waitcnt lgkmcnt(1)
	v_add_f32_e32 v4, v4, v6
	v_cndmask_b32_e32 v8, v209, v13, vcc
	v_lshlrev_b32_e32 v8, 2, v8
	s_waitcnt lgkmcnt(0)
	v_add_f32_e32 v5, v5, v7
	ds_bpermute_b32 v6, v8, v4
	ds_bpermute_b32 v7, v8, v5
	s_andn2_b64 vcc, exec, s[4:5]
	s_cbranch_vccnz .LBB0_383
	s_waitcnt lgkmcnt(1)
	v_add_f32_e32 v4, v4, v6
	s_waitcnt lgkmcnt(0)
	v_add_f32_e32 v5, v5, v7
	s_load_dwordx2 s[2:3], s[76:77], 0xe8
	v_mul_f32_e32 v4, 0x3fb8aa3b, v4
	v_mul_f32_e32 v5, 0x3fb8aa3b, v5
	v_exp_f32_e32 v4, v4
	v_exp_f32_e32 v5, v5
	s_waitcnt lgkmcnt(0)
	s_add_u32 s0, s2, 0x9300000
	v_lshlrev_b32_e32 v6, 4, v2
	v_writelane_b32 v255, s0, 2
	v_sub_f32_e32 v4, v4, v5
	s_addc_u32 s0, s3, 0
	v_add_f32_e32 v151, 0x3eb60549, v4
	v_lshlrev_b32_e32 v4, 3, v2
	v_and_b32_e32 v6, 0xc0, v6
	v_lshlrev_b32_e32 v7, 1, v2
	s_add_i32 s96, 0, 0x10000
	v_and_or_b32 v6, v4, 24, v6
	v_and_b32_e32 v7, 32, v7
	v_and_b32_e32 v4, 0x100, v4
	s_cmp_lg_u32 s96, -1
	v_or3_b32 v4, v6, v7, v4
	s_cselect_b32 s4, s96, 0
	v_lshlrev_b32_e32 v6, 3, v1
	v_ashrrev_i32_e32 v5, 4, v3
	v_add_u32_e32 v153, s4, v4
	v_and_b32_e32 v4, 0x78, v6
	v_lshlrev_b32_e32 v8, 1, v4
	v_and_b32_e32 v3, 0x70, v3
	v_lshlrev_b32_e32 v9, 8, v5
	v_bitop3_b32 v9, v8, v9, v3 bitop3:0xde
	v_add_u32_e32 v3, 32, v5
	v_lshlrev_b32_e32 v10, 1, v3
	v_and_b32_e32 v3, 0xfffff0, v3
	v_and_or_b32 v3, v10, 8, v3
	v_lshrrev_b32_e32 v3, 1, v3
	v_bfe_u32 v6, v6, 5, 2
	v_lshrrev_b32_e32 v10, 1, v5
	v_and_b32_e32 v11, 3, v5
	v_or_b32_e32 v3, v3, v6
	v_and_or_b32 v10, v10, 4, v11
	v_lshlrev_b32_e32 v3, 9, v3
	v_lshlrev_b32_e32 v10, 6, v10
	v_and_b32_e32 v8, 48, v8
	v_or3_b32 v155, v3, v10, v8
	v_lshlrev_b32_e32 v3, 1, v5
	v_and_b32_e32 v11, 0xfffff0, v5
	v_and_or_b32 v3, v3, 8, v11
	v_lshrrev_b32_e32 v3, 1, v3
	s_and_b32 s4, s6, 0x3fffffc0
	v_or_b32_e32 v3, v3, v6
	s_lshl_b32 s4, s4, 2
	v_lshlrev_b32_e32 v3, 9, v3
	v_writelane_b32 v255, s0, 3
	s_add_i32 s4, s4, 0
	v_or3_b32 v157, v3, v10, v8
	s_movk_i32 s0, 0x1800
	v_add_u32_e32 v3, 64, v5
	s_add_i32 s10, s4, 0x20000
	s_bfe_u32 s11, s6, 0x10006
	v_mad_i64_i32 v[132:133], s[4:5], v5, s0, 0
	v_mad_i64_i32 v[134:135], s[4:5], v3, s0, 0
	s_lshl_b32 s4, s11, 7
	v_and_b32_e32 v149, 31, v1
	v_lshrrev_b32_e32 v7, 5, v2
	s_add_i32 s4, s4, 0
	s_ashr_i32 s7, s6, 7
	v_lshlrev_b32_e32 v8, 4, v7
	v_lshlrev_b32_e32 v3, 4, v1
	v_lshl_add_u32 v11, v149, 8, s4
	s_movk_i32 s4, 0x70
	s_lshl_b32 s97, s7, 5
	s_lshl_b32 s100, s11, 10
	s_lshl_b32 s101, s7, 11
	s_add_u32 s100, s100, s101
	s_lshr_b32 s101, s100, 4
	s_and_b32 s101, s101, 0xc0
	v_and_b32_e32 v10, 0x70, v3
	v_bitop3_b32 v12, v8, v3, s4 bitop3:0x78
	s_movk_i32 s4, 0x60
	s_lshl_b32 s7, s7, 14
	s_lshl_b32 s12, s11, 6
	v_bitop3_b32 v13, v8, v10, 32 bitop3:0x36
	v_bitop3_b32 v14, v8, v10, 64 bitop3:0x36
	v_bitop3_b32 v10, v8, v10, s4 bitop3:0x36
	v_cmp_gt_u32_e64 s[4:5], 32, v2
	v_lshlrev_b32_e32 v2, 2, v149
	s_add_i32 s7, s7, 0
	s_and_b32 s6, 64, s6
	v_add_u32_e32 v159, s10, v2
	v_add_u32_e32 v3, 0x80, v5
	s_cmp_eq_u32 s11, 0
	v_add_u32_e32 v5, s7, v2
	v_and_b32_e32 v2, 1, v1
	v_mad_i64_i32 v[136:137], s[8:9], v3, s0, 0
	s_cselect_b64 s[82:83], -1, 0
	s_cmp_lg_u32 s6, 0
	v_cmp_eq_u32_e64 s[6:7], 0, v2
	v_lshlrev_b32_e32 v2, 1, v149
	v_mov_b32_e32 v3, v0
	v_lshlrev_b32_e32 v130, 2, v7
	v_lshl_add_u64 v[2:3], s[2:3], 0, v[2:3]
	s_mov_b64 s[8:9], 0x15300000
	v_and_b32_e32 v1, 15, v1
	s_cselect_b64 s[76:77], -1, 0
	v_lshl_add_u64 v[138:139], v[2:3], 0, s[8:9]
	v_or_b32_e32 v140, 1, v130
	v_or_b32_e32 v142, 2, v130
	v_or_b32_e32 v144, 3, v130
	v_or_b32_e32 v146, 8, v130
	v_or_b32_e32 v148, 9, v130
	v_or_b32_e32 v150, 10, v130
	v_or_b32_e32 v152, 11, v130
	v_or_b32_e32 v154, 16, v130
	v_or_b32_e32 v156, 17, v130
	v_or_b32_e32 v158, 18, v130
	v_or_b32_e32 v160, 19, v130
	v_or_b32_e32 v162, 24, v130
	v_or_b32_e32 v164, 25, v130
	v_or_b32_e32 v166, 26, v130
	v_or_b32_e32 v168, 27, v130
	v_lshl_or_b32 v2, v1, 4, v132
	v_mov_b32_e32 v3, v133
	s_lshl_b32 s0, s12, 1
	v_lshlrev_b32_e32 v6, 3, v7
	v_add_u32_e32 v161, s10, v8
	v_lshl_add_u32 v163, v7, 11, v5
	v_lshlrev_b32_e32 v7, 9, v140
	v_lshlrev_b32_e32 v8, 9, v142
	v_lshlrev_b32_e32 v15, 9, v144
	v_lshlrev_b32_e32 v16, 9, v146
	v_lshlrev_b32_e32 v17, 9, v148
	v_lshlrev_b32_e32 v18, 9, v150
	v_lshlrev_b32_e32 v19, 9, v152
	v_lshlrev_b32_e32 v20, 9, v154
	v_lshlrev_b32_e32 v21, 9, v156
	v_lshlrev_b32_e32 v22, 9, v158
	v_lshlrev_b32_e32 v23, 9, v160
	v_lshlrev_b32_e32 v24, 9, v162
	v_lshlrev_b32_e32 v25, 9, v164
	v_lshlrev_b32_e32 v26, 9, v166
	v_lshlrev_b32_e32 v27, 9, v168
	v_lshl_add_u64 v[2:3], s[2:3], 0, v[2:3]
	s_mov_b64 s[2:3], 0x9571000
	v_writelane_b32 v255, s0, 4
	v_lshl_add_u64 v[170:171], v[2:3], 0, s[2:3]
	v_lshlrev_b32_e32 v172, 1, v6
	v_lshlrev_b32_e32 v174, 1, v4
	v_add_u32_e32 v165, v5, v7
	v_add_u32_e32 v167, v5, v8
	v_add_u32_e32 v169, v5, v15
	v_add_u32_e32 v202, v5, v16
	v_add_u32_e32 v203, v5, v17
	v_add_u32_e32 v204, v5, v18
	v_add_u32_e32 v205, v5, v19
	v_add_u32_e32 v216, v5, v20
	v_add_u32_e32 v217, v5, v21
	v_add_u32_e32 v218, v5, v22
	v_add_u32_e32 v219, v5, v23
	v_add_u32_e32 v220, v5, v24
	v_add_u32_e32 v221, v5, v25
	v_add_u32_e32 v222, v5, v26
	v_add_u32_e32 v223, v5, v27
	v_add_u32_e32 v224, 0, v9
	v_add_u32_e32 v225, v11, v12
	v_add_u32_e32 v226, v11, v13
	v_add_u32_e32 v227, v11, v14
	v_add_u32_e32 v228, v11, v10
	v_bfe_u32 v250, v224, 11, 1
	v_bfe_u32 v251, v149, 3, 1
	v_lshlrev_b32_e32 v250, 7, v250
	v_lshlrev_b32_e32 v251, 7, v251
	v_xor_b32_e32 v224, v224, v250
	v_xor_b32_e32 v225, v225, v251
	v_xor_b32_e32 v226, v226, v251
	v_xor_b32_e32 v227, v227, v251
	v_xor_b32_e32 v228, v228, v251
	v_readlane_b32 s0, v254, 33
	v_readlane_b32 s94, v254, 53
	v_writelane_b32 v255, s73, 5
	s_branch .LBB0_159

.LBB0_175:
	v_cndmask_b32_e64 v233, v234, v233, s[8:9]
	v_mul_f32_e32 v206, 0xbe38aa3b, v233
	v_fmamk_f32 v82, v82, 0x3e38aa3b, v206
	v_fmamk_f32 v83, v83, 0x3e38aa3b, v206
	v_fmamk_f32 v84, v84, 0x3e38aa3b, v206
	v_fmamk_f32 v85, v85, 0x3e38aa3b, v206
	v_fmamk_f32 v86, v86, 0x3e38aa3b, v206
	v_fmamk_f32 v87, v87, 0x3e38aa3b, v206
	v_fmamk_f32 v88, v88, 0x3e38aa3b, v206
	v_fmamk_f32 v89, v89, 0x3e38aa3b, v206
	v_fmamk_f32 v90, v90, 0x3e38aa3b, v206
	v_fmamk_f32 v91, v91, 0x3e38aa3b, v206
	v_fmamk_f32 v92, v92, 0x3e38aa3b, v206
	v_fmamk_f32 v93, v93, 0x3e38aa3b, v206
	v_fmamk_f32 v94, v94, 0x3e38aa3b, v206
	v_fmamk_f32 v95, v95, 0x3e38aa3b, v206
	v_fmamk_f32 v96, v96, 0x3e38aa3b, v206
	v_fmamk_f32 v97, v97, 0x3e38aa3b, v206
	v_fmamk_f32 v66, v66, 0x3e38aa3b, v206
	v_fmamk_f32 v67, v67, 0x3e38aa3b, v206
	v_fmamk_f32 v68, v68, 0x3e38aa3b, v206
	v_fmamk_f32 v69, v69, 0x3e38aa3b, v206
	v_fmamk_f32 v70, v70, 0x3e38aa3b, v206
	v_fmamk_f32 v71, v71, 0x3e38aa3b, v206
	v_fmamk_f32 v72, v72, 0x3e38aa3b, v206
	v_fmamk_f32 v73, v73, 0x3e38aa3b, v206
	v_fmamk_f32 v74, v74, 0x3e38aa3b, v206
	v_fmamk_f32 v75, v75, 0x3e38aa3b, v206
	v_fmamk_f32 v76, v76, 0x3e38aa3b, v206
	v_fmamk_f32 v77, v77, 0x3e38aa3b, v206
	v_fmamk_f32 v78, v78, 0x3e38aa3b, v206
	v_fmamk_f32 v79, v79, 0x3e38aa3b, v206
	v_fmamk_f32 v80, v80, 0x3e38aa3b, v206
	v_fmac_f32_e32 v206, 0x3e38aa3b, v81
	v_exp_f32_e32 v81, v82
	v_exp_f32_e32 v82, v83
	v_exp_f32_e32 v83, v84
	v_exp_f32_e32 v84, v85
	v_exp_f32_e32 v85, v86
	v_exp_f32_e32 v86, v87
	v_exp_f32_e32 v87, v88
	v_exp_f32_e32 v88, v89
	v_exp_f32_e32 v89, v90
	v_exp_f32_e32 v90, v91
	v_exp_f32_e32 v91, v92
	v_exp_f32_e32 v92, v93
	v_exp_f32_e32 v93, v94
	v_exp_f32_e32 v94, v95
	v_exp_f32_e32 v95, v96
	v_exp_f32_e32 v96, v97
	v_exp_f32_e32 v97, v66
	v_add_f32_e32 v66, 0, v81
	v_add_f32_e32 v66, v82, v66
	v_add_f32_e32 v66, v83, v66
	v_add_f32_e32 v66, v84, v66
	v_add_f32_e32 v66, v85, v66
	v_add_f32_e32 v66, v86, v66
	v_add_f32_e32 v66, v87, v66
	v_add_f32_e32 v66, v88, v66
	v_add_f32_e32 v66, v89, v66
	v_add_f32_e32 v66, v90, v66
	v_add_f32_e32 v66, v91, v66
	v_add_f32_e32 v66, v92, v66
	v_add_f32_e32 v66, v93, v66
	v_exp_f32_e32 v212, v67
	v_add_f32_e32 v66, v94, v66
	v_exp_f32_e32 v213, v68
	v_add_f32_e32 v66, v95, v66
	v_exp_f32_e32 v214, v69
	v_add_f32_e32 v66, v96, v66
	v_exp_f32_e32 v215, v70
	v_add_f32_e32 v66, v97, v66
	v_exp_f32_e32 v236, v71
	v_add_f32_e32 v66, v212, v66
	v_exp_f32_e32 v237, v72
	v_add_f32_e32 v66, v213, v66
	v_exp_f32_e32 v238, v73
	v_add_f32_e32 v66, v214, v66
	v_exp_f32_e32 v239, v74
	v_add_f32_e32 v66, v215, v66
	v_exp_f32_e32 v240, v75
	v_add_f32_e32 v66, v236, v66
	v_exp_f32_e32 v241, v76
	v_add_f32_e32 v66, v237, v66
	v_exp_f32_e32 v242, v77
	v_add_f32_e32 v66, v238, v66
	v_exp_f32_e32 v243, v78
	v_add_f32_e32 v66, v239, v66
	v_exp_f32_e32 v244, v79
	v_add_f32_e32 v66, v240, v66
	v_exp_f32_e32 v245, v80
	v_add_f32_e32 v66, v241, v66
	v_exp_f32_e32 v206, v206
	v_add_f32_e32 v66, v242, v66
	v_add_f32_e32 v66, v243, v66
	v_add_f32_e32 v66, v244, v66
	v_add_f32_e32 v66, v245, v66
	v_add_f32_e32 v234, v206, v66
	v_mov_b32_e32 v235, v234
	s_nop 1
	v_permlane32_swap_b32_e32 v234, v235
	v_cvt_pk_bf16_f32 v66, v81, v82
	v_cvt_pk_bf16_f32 v67, v83, v84
	v_cvt_pk_bf16_f32 v68, v85, v86
	v_cvt_pk_bf16_f32 v69, v87, v88
	v_cvt_pk_bf16_f32 v70, v89, v90
	v_cvt_pk_bf16_f32 v71, v91, v92
	v_cvt_pk_bf16_f32 v72, v93, v94
	v_cvt_pk_bf16_f32 v73, v95, v96
	v_cvt_pk_bf16_f32 v74, v97, v212
	ds_read_b64_tr_b16 v[82:83], v153 offset:0
	ds_read_b64_tr_b16 v[84:85], v153 offset:0x800
	ds_read_b64_tr_b16 v[86:87], v153 offset:0x1000
	ds_read_b64_tr_b16 v[88:89], v153 offset:0x1800
	ds_read_b64_tr_b16 v[90:91], v153 offset:0x2000
	ds_read_b64_tr_b16 v[92:93], v153 offset:0x2800
	ds_read_b64_tr_b16 v[94:95], v153 offset:0x3000
	ds_read_b64_tr_b16 v[96:97], v153 offset:0x3800
	v_cvt_pk_bf16_f32 v75, v213, v214
	v_cvt_pk_bf16_f32 v76, v215, v236
	v_cvt_pk_bf16_f32 v77, v237, v238
	v_cvt_pk_bf16_f32 v78, v239, v240
	v_cvt_pk_bf16_f32 v79, v241, v242
	v_cvt_pk_bf16_f32 v80, v243, v244
	v_cvt_pk_bf16_f32 v81, v245, v206
	s_nop 0
	v_permlane32_swap_b32_e32 v66, v68
	v_permlane32_swap_b32_e32 v67, v69
	v_permlane32_swap_b32_e32 v70, v72
	v_permlane32_swap_b32_e32 v71, v73
	v_permlane32_swap_b32_e32 v74, v76
	v_permlane32_swap_b32_e32 v75, v77
	v_permlane32_swap_b32_e32 v78, v80
	v_permlane32_swap_b32_e32 v79, v81
	s_nop 0
	s_waitcnt lgkmcnt(6)
	v_mfma_f32_32x32x16_bf16 v[50:65], v[66:69], v[82:85], v[50:65]
	ds_read_b64_tr_b16 v[82:83], v153 offset:0x200
	ds_read_b64_tr_b16 v[84:85], v153 offset:0xa00
	s_waitcnt lgkmcnt(6)
	v_mfma_f32_32x32x16_bf16 v[50:65], v[70:73], v[86:89], v[50:65]
	ds_read_b64_tr_b16 v[86:87], v153 offset:0x1200
	ds_read_b64_tr_b16 v[88:89], v153 offset:0x1a00
	s_waitcnt lgkmcnt(6)
	v_mfma_f32_32x32x16_bf16 v[50:65], v[74:77], v[90:93], v[50:65]
	ds_read_b64_tr_b16 v[90:91], v153 offset:0x2200
	ds_read_b64_tr_b16 v[92:93], v153 offset:0x2a00
	s_waitcnt lgkmcnt(6)
	v_mfma_f32_32x32x16_bf16 v[50:65], v[78:81], v[94:97], v[50:65]
	s_andn2_b64 vcc, exec, s[38:39]
	s_cbranch_vccnz .Lattn_sw0
	v_add_u32_e32 v250, s84, v157
	s_waitcnt vmcnt(1)
	ds_write_b128 v250, v[118:121]
	v_add_u32_e32 v250, s84, v155
	s_waitcnt vmcnt(0)
	ds_write_b128 v250, v[126:129]
	v_and_b32_e32 v252, 48, v209
	v_or_b32_e32 v252, s101, v252
	v_add_co_u32_e32 v250, vcc, 0xffe4f800, v200
	s_nop 1
	v_addc_co_u32_e32 v251, vcc, -1, v201, vcc
	v_xor_b32_e32 v250, v250, v252
	s_add_u32 m0, s100, 0x8000
	s_nop 0
	global_load_lds_dwordx4 v[250:251], off
	v_add_co_u32_e32 v250, vcc, 0xffe7f800, v200
	s_nop 1
	v_addc_co_u32_e32 v251, vcc, -1, v201, vcc
	v_xor_b32_e32 v250, v250, v252
	s_add_u32 m0, s100, 0xa000
	s_nop 0
	global_load_lds_dwordx4 v[250:251], off
.Lattn_sw0:
	s_add_i32 s80, s99, 3
	s_cmp_lt_u32 s80, s79
	s_cselect_b64 s[72:73], -1, 0
	s_cmp_ge_u32 s80, s79
	s_cbranch_scc1 .Lattn_sl0
	v_and_b32_e32 v252, 48, v209
	v_or_b32_e32 v252, s101, v252
	v_add_co_u32_e32 v250, vcc, 0xffeaf800, v200
	s_nop 1
	v_addc_co_u32_e32 v251, vcc, -1, v201, vcc
	v_xor_b32_e32 v250, v250, v252
	s_add_u32 m0, s100, 0xc000
	s_nop 0
	global_load_lds_dwordx4 v[250:251], off
	v_add_co_u32_e32 v250, vcc, 0xffedf800, v200
	s_nop 1
	v_addc_co_u32_e32 v251, vcc, -1, v201, vcc
	v_xor_b32_e32 v250, v250, v252
	s_add_u32 m0, s100, 0xe000
	s_nop 0
	global_load_lds_dwordx4 v[250:251], off
	v_add_co_u32_e32 v250, vcc, 0xffeb0000, v200
	s_nop 1
	v_addc_co_u32_e32 v251, vcc, -1, v201, vcc
	global_load_dwordx4 v[118:121], v[250:251], off
	v_add_co_u32_e32 v250, vcc, 0xffee0000, v200
	s_nop 1
	v_addc_co_u32_e32 v251, vcc, -1, v201, vcc
	global_load_dwordx4 v[126:129], v[250:251], off

.LBB0_185:
	v_cndmask_b32_e64 v233, v237, v233, s[8:9]
	v_mul_f32_e32 v206, 0xbe38aa3b, v233
	v_fmamk_f32 v82, v82, 0x3e38aa3b, v206
	v_fmamk_f32 v83, v83, 0x3e38aa3b, v206
	v_fmamk_f32 v84, v84, 0x3e38aa3b, v206
	v_fmamk_f32 v85, v85, 0x3e38aa3b, v206
	v_fmamk_f32 v86, v86, 0x3e38aa3b, v206
	v_fmamk_f32 v87, v87, 0x3e38aa3b, v206
	v_fmamk_f32 v88, v88, 0x3e38aa3b, v206
	v_fmamk_f32 v89, v89, 0x3e38aa3b, v206
	v_fmamk_f32 v90, v90, 0x3e38aa3b, v206
	v_fmamk_f32 v91, v91, 0x3e38aa3b, v206
	v_fmamk_f32 v92, v92, 0x3e38aa3b, v206
	v_fmamk_f32 v93, v93, 0x3e38aa3b, v206
	v_fmamk_f32 v94, v94, 0x3e38aa3b, v206
	v_fmamk_f32 v95, v95, 0x3e38aa3b, v206
	v_fmamk_f32 v96, v96, 0x3e38aa3b, v206
	v_fmamk_f32 v97, v97, 0x3e38aa3b, v206
	v_fmamk_f32 v66, v66, 0x3e38aa3b, v206
	v_fmamk_f32 v67, v67, 0x3e38aa3b, v206
	v_fmamk_f32 v68, v68, 0x3e38aa3b, v206
	v_fmamk_f32 v69, v69, 0x3e38aa3b, v206
	v_fmamk_f32 v70, v70, 0x3e38aa3b, v206
	v_fmamk_f32 v71, v71, 0x3e38aa3b, v206
	v_fmamk_f32 v72, v72, 0x3e38aa3b, v206
	v_fmamk_f32 v73, v73, 0x3e38aa3b, v206
	v_fmamk_f32 v74, v74, 0x3e38aa3b, v206
	v_fmamk_f32 v75, v75, 0x3e38aa3b, v206
	v_fmamk_f32 v76, v76, 0x3e38aa3b, v206
	v_fmamk_f32 v77, v77, 0x3e38aa3b, v206
	v_fmamk_f32 v78, v78, 0x3e38aa3b, v206
	v_fmamk_f32 v79, v79, 0x3e38aa3b, v206
	v_fmamk_f32 v80, v80, 0x3e38aa3b, v206
	v_fmac_f32_e32 v206, 0x3e38aa3b, v81
	v_exp_f32_e32 v81, v82
	v_exp_f32_e32 v82, v83
	v_exp_f32_e32 v83, v84
	v_exp_f32_e32 v84, v85
	v_exp_f32_e32 v85, v86
	v_exp_f32_e32 v86, v87
	v_exp_f32_e32 v87, v88
	v_exp_f32_e32 v88, v89
	v_exp_f32_e32 v89, v90
	v_exp_f32_e32 v90, v91
	v_exp_f32_e32 v91, v92
	v_exp_f32_e32 v92, v93
	v_exp_f32_e32 v93, v94
	v_exp_f32_e32 v94, v95
	v_exp_f32_e32 v95, v96
	v_exp_f32_e32 v96, v97
	v_add_f32_e32 v97, v234, v235
	v_fmac_f32_e32 v97, v232, v1
	v_exp_f32_e32 v1, v66
	v_add_f32_e32 v66, 0, v81
	v_add_f32_e32 v66, v82, v66
	v_add_f32_e32 v66, v83, v66
	v_add_f32_e32 v66, v84, v66
	v_add_f32_e32 v66, v85, v66
	v_add_f32_e32 v66, v86, v66
	v_add_f32_e32 v66, v87, v66
	v_add_f32_e32 v66, v88, v66
	v_add_f32_e32 v66, v89, v66
	v_add_f32_e32 v66, v90, v66
	v_add_f32_e32 v66, v91, v66
	v_add_f32_e32 v66, v92, v66
	v_add_f32_e32 v66, v93, v66
	v_exp_f32_e32 v212, v67
	v_add_f32_e32 v66, v94, v66
	v_exp_f32_e32 v213, v68
	v_add_f32_e32 v66, v95, v66
	v_exp_f32_e32 v214, v69
	v_add_f32_e32 v66, v96, v66
	v_exp_f32_e32 v215, v70
	v_add_f32_e32 v66, v1, v66
	v_exp_f32_e32 v234, v71
	v_add_f32_e32 v66, v212, v66
	v_exp_f32_e32 v235, v72
	v_add_f32_e32 v66, v213, v66
	v_exp_f32_e32 v237, v73
	v_add_f32_e32 v66, v214, v66
	v_exp_f32_e32 v238, v74
	v_add_f32_e32 v66, v215, v66
	v_exp_f32_e32 v239, v75
	v_add_f32_e32 v66, v234, v66
	v_exp_f32_e32 v240, v76
	v_add_f32_e32 v66, v235, v66
	v_exp_f32_e32 v241, v77
	v_add_f32_e32 v66, v237, v66
	v_exp_f32_e32 v242, v78
	v_add_f32_e32 v66, v238, v66
	v_exp_f32_e32 v243, v79
	v_add_f32_e32 v66, v239, v66
	v_exp_f32_e32 v244, v80
	v_add_f32_e32 v66, v240, v66
	v_exp_f32_e32 v206, v206
	v_add_f32_e32 v66, v241, v66
	v_add_f32_e32 v66, v242, v66
	v_add_f32_e32 v66, v243, v66
	v_add_f32_e32 v66, v244, v66
	v_add_f32_e32 v66, v206, v66
	v_mov_b32_e32 v67, v66
	s_nop 1
	v_permlane32_swap_b32_e32 v66, v67
	v_add_f32_e32 v232, v66, v67
	v_fmac_f32_e32 v232, v97, v236
	v_cvt_pk_bf16_f32 v66, v81, v82
	v_cvt_pk_bf16_f32 v67, v83, v84
	v_cvt_pk_bf16_f32 v68, v85, v86
	v_cvt_pk_bf16_f32 v69, v87, v88
	v_cvt_pk_bf16_f32 v70, v89, v90
	v_cvt_pk_bf16_f32 v71, v91, v92
	v_cvt_pk_bf16_f32 v72, v93, v94
	v_cvt_pk_bf16_f32 v73, v95, v96
	ds_read_b64_tr_b16 v[82:83], v153 offset:0x4000
	ds_read_b64_tr_b16 v[84:85], v153 offset:0x4800
	ds_read_b64_tr_b16 v[86:87], v153 offset:0x5000
	ds_read_b64_tr_b16 v[88:89], v153 offset:0x5800
	ds_read_b64_tr_b16 v[90:91], v153 offset:0x6000
	ds_read_b64_tr_b16 v[92:93], v153 offset:0x6800
	ds_read_b64_tr_b16 v[94:95], v153 offset:0x7000
	ds_read_b64_tr_b16 v[96:97], v153 offset:0x7800
	v_cvt_pk_bf16_f32 v74, v1, v212
	v_cvt_pk_bf16_f32 v75, v213, v214
	v_cvt_pk_bf16_f32 v76, v215, v234
	v_cvt_pk_bf16_f32 v77, v235, v237
	v_cvt_pk_bf16_f32 v78, v238, v239
	v_cvt_pk_bf16_f32 v79, v240, v241
	v_cvt_pk_bf16_f32 v80, v242, v243
	v_cvt_pk_bf16_f32 v81, v244, v206
	s_nop 0
	v_permlane32_swap_b32_e32 v66, v68
	v_permlane32_swap_b32_e32 v67, v69
	v_permlane32_swap_b32_e32 v70, v72
	v_permlane32_swap_b32_e32 v71, v73
	v_permlane32_swap_b32_e32 v74, v76
	v_permlane32_swap_b32_e32 v75, v77
	v_permlane32_swap_b32_e32 v78, v80
	v_permlane32_swap_b32_e32 v79, v81
	s_nop 0
	s_waitcnt lgkmcnt(6)
	v_mfma_f32_32x32x16_bf16 v[50:65], v[66:69], v[82:85], v[50:65]
	ds_read_b64_tr_b16 v[82:83], v153 offset:0x4200
	ds_read_b64_tr_b16 v[84:85], v153 offset:0x4a00
	s_waitcnt lgkmcnt(6)
	v_mfma_f32_32x32x16_bf16 v[50:65], v[70:73], v[86:89], v[50:65]
	ds_read_b64_tr_b16 v[86:87], v153 offset:0x5200
	ds_read_b64_tr_b16 v[88:89], v153 offset:0x5a00
	s_waitcnt lgkmcnt(6)
	v_mfma_f32_32x32x16_bf16 v[50:65], v[74:77], v[90:93], v[50:65]
	ds_read_b64_tr_b16 v[90:91], v153 offset:0x6200
	ds_read_b64_tr_b16 v[92:93], v153 offset:0x6a00
	s_waitcnt lgkmcnt(6)
	v_mfma_f32_32x32x16_bf16 v[50:65], v[78:81], v[94:97], v[50:65]
	s_andn2_b64 vcc, exec, s[72:73]
	s_cbranch_vccnz .Lattn_sw1
	v_add_u32_e32 v250, s88, v157
	s_waitcnt vmcnt(1)
	ds_write_b128 v250, v[118:121]
	v_add_u32_e32 v250, s88, v155
	s_waitcnt vmcnt(0)
	ds_write_b128 v250, v[126:129]
.Lattn_sw1:
	s_add_i32 s80, s80, 1
	s_cmp_le_u32 s80, s33
	s_cselect_b64 s[72:73], -1, 0
	s_cmp_gt_u32 s80, s33
	s_cbranch_scc1 .Lattn_sl1
	v_add_co_u32_e32 v250, vcc, 0xfff10000, v200
	s_nop 1
	v_addc_co_u32_e32 v251, vcc, -1, v201, vcc
	global_load_dwordx4 v[118:121], v[250:251], off
	v_add_co_u32_e32 v250, vcc, 0xfff40000, v200
	s_nop 1
	v_addc_co_u32_e32 v251, vcc, -1, v201, vcc
	global_load_dwordx4 v[126:129], v[250:251], off

.LBB0_196:
	v_cndmask_b32_e64 v233, v234, v233, s[8:9]
	v_mul_f32_e32 v206, 0xbe38aa3b, v233
	v_fmamk_f32 v82, v82, 0x3e38aa3b, v206
	v_fmamk_f32 v83, v83, 0x3e38aa3b, v206
	v_fmamk_f32 v84, v84, 0x3e38aa3b, v206
	v_fmamk_f32 v85, v85, 0x3e38aa3b, v206
	v_fmamk_f32 v86, v86, 0x3e38aa3b, v206
	v_fmamk_f32 v87, v87, 0x3e38aa3b, v206
	v_fmamk_f32 v88, v88, 0x3e38aa3b, v206
	v_fmamk_f32 v89, v89, 0x3e38aa3b, v206
	v_fmamk_f32 v90, v90, 0x3e38aa3b, v206
	v_fmamk_f32 v91, v91, 0x3e38aa3b, v206
	v_fmamk_f32 v92, v92, 0x3e38aa3b, v206
	v_fmamk_f32 v93, v93, 0x3e38aa3b, v206
	v_fmamk_f32 v94, v94, 0x3e38aa3b, v206
	v_fmamk_f32 v95, v95, 0x3e38aa3b, v206
	v_fmamk_f32 v96, v96, 0x3e38aa3b, v206
	v_fmamk_f32 v97, v97, 0x3e38aa3b, v206
	v_fmamk_f32 v66, v66, 0x3e38aa3b, v206
	v_fmamk_f32 v67, v67, 0x3e38aa3b, v206
	v_fmamk_f32 v68, v68, 0x3e38aa3b, v206
	v_fmamk_f32 v69, v69, 0x3e38aa3b, v206
	v_fmamk_f32 v70, v70, 0x3e38aa3b, v206
	v_fmamk_f32 v71, v71, 0x3e38aa3b, v206
	v_fmamk_f32 v72, v72, 0x3e38aa3b, v206
	v_fmamk_f32 v73, v73, 0x3e38aa3b, v206
	v_fmamk_f32 v74, v74, 0x3e38aa3b, v206
	v_fmamk_f32 v75, v75, 0x3e38aa3b, v206
	v_fmamk_f32 v76, v76, 0x3e38aa3b, v206
	v_fmamk_f32 v77, v77, 0x3e38aa3b, v206
	v_fmamk_f32 v78, v78, 0x3e38aa3b, v206
	v_fmamk_f32 v79, v79, 0x3e38aa3b, v206
	v_fmamk_f32 v80, v80, 0x3e38aa3b, v206
	v_fmac_f32_e32 v206, 0x3e38aa3b, v81
	v_exp_f32_e32 v81, v82
	v_exp_f32_e32 v82, v83
	v_exp_f32_e32 v83, v84
	v_exp_f32_e32 v84, v85
	v_exp_f32_e32 v85, v86
	v_exp_f32_e32 v86, v87
	v_exp_f32_e32 v87, v88
	v_exp_f32_e32 v88, v89
	v_exp_f32_e32 v89, v90
	v_exp_f32_e32 v90, v91
	v_exp_f32_e32 v91, v92
	v_exp_f32_e32 v92, v93
	v_exp_f32_e32 v93, v94
	v_exp_f32_e32 v94, v95
	v_exp_f32_e32 v95, v96
	v_exp_f32_e32 v96, v97
	v_exp_f32_e32 v97, v66
	v_add_f32_e32 v66, 0, v81
	v_add_f32_e32 v66, v82, v66
	v_add_f32_e32 v66, v83, v66
	v_add_f32_e32 v66, v84, v66
	v_add_f32_e32 v66, v85, v66
	v_add_f32_e32 v66, v86, v66
	v_add_f32_e32 v66, v87, v66
	v_add_f32_e32 v66, v88, v66
	v_add_f32_e32 v66, v89, v66
	v_add_f32_e32 v66, v90, v66
	v_add_f32_e32 v66, v91, v66
	v_add_f32_e32 v66, v92, v66
	v_add_f32_e32 v66, v93, v66
	v_exp_f32_e32 v212, v67
	v_add_f32_e32 v66, v94, v66
	v_exp_f32_e32 v213, v68
	v_add_f32_e32 v66, v95, v66
	v_exp_f32_e32 v214, v69
	v_add_f32_e32 v66, v96, v66
	v_exp_f32_e32 v215, v70
	v_add_f32_e32 v66, v97, v66
	v_exp_f32_e32 v236, v71
	v_add_f32_e32 v66, v212, v66
	v_exp_f32_e32 v237, v72
	v_add_f32_e32 v66, v213, v66
	v_exp_f32_e32 v238, v73
	v_add_f32_e32 v66, v214, v66
	v_exp_f32_e32 v239, v74
	v_add_f32_e32 v66, v215, v66
	v_exp_f32_e32 v240, v75
	v_add_f32_e32 v66, v236, v66
	v_exp_f32_e32 v241, v76
	v_add_f32_e32 v66, v237, v66
	v_exp_f32_e32 v242, v77
	v_add_f32_e32 v66, v238, v66
	v_exp_f32_e32 v243, v78
	v_add_f32_e32 v66, v239, v66
	v_exp_f32_e32 v244, v79
	v_add_f32_e32 v66, v240, v66
	v_exp_f32_e32 v245, v80
	v_add_f32_e32 v66, v241, v66
	v_exp_f32_e32 v206, v206
	v_add_f32_e32 v66, v242, v66
	v_add_f32_e32 v66, v243, v66
	v_add_f32_e32 v66, v244, v66
	v_add_f32_e32 v66, v245, v66
	v_add_f32_e32 v234, v206, v66
	v_mov_b32_e32 v235, v234
	s_nop 1
	v_permlane32_swap_b32_e32 v234, v235
	v_cvt_pk_bf16_f32 v66, v81, v82
	v_cvt_pk_bf16_f32 v67, v83, v84
	v_cvt_pk_bf16_f32 v68, v85, v86
	v_cvt_pk_bf16_f32 v69, v87, v88
	v_cvt_pk_bf16_f32 v70, v89, v90
	v_cvt_pk_bf16_f32 v71, v91, v92
	v_cvt_pk_bf16_f32 v72, v93, v94
	v_cvt_pk_bf16_f32 v73, v95, v96
	v_cvt_pk_bf16_f32 v74, v97, v212
	ds_read_b64_tr_b16 v[82:83], v153 offset:0x8000
	ds_read_b64_tr_b16 v[84:85], v153 offset:0x8800
	ds_read_b64_tr_b16 v[86:87], v153 offset:0x9000
	ds_read_b64_tr_b16 v[88:89], v153 offset:0x9800
	ds_read_b64_tr_b16 v[90:91], v153 offset:0xa000
	ds_read_b64_tr_b16 v[92:93], v153 offset:0xa800
	ds_read_b64_tr_b16 v[94:95], v153 offset:0xb000
	ds_read_b64_tr_b16 v[96:97], v153 offset:0xb800
	v_cvt_pk_bf16_f32 v75, v213, v214
	v_cvt_pk_bf16_f32 v76, v215, v236
	v_cvt_pk_bf16_f32 v77, v237, v238
	v_cvt_pk_bf16_f32 v78, v239, v240
	v_cvt_pk_bf16_f32 v79, v241, v242
	v_cvt_pk_bf16_f32 v80, v243, v244
	v_cvt_pk_bf16_f32 v81, v245, v206
	s_nop 0
	v_permlane32_swap_b32_e32 v66, v68
	v_permlane32_swap_b32_e32 v67, v69
	v_permlane32_swap_b32_e32 v70, v72
	v_permlane32_swap_b32_e32 v71, v73
	v_permlane32_swap_b32_e32 v74, v76
	v_permlane32_swap_b32_e32 v75, v77
	v_permlane32_swap_b32_e32 v78, v80
	v_permlane32_swap_b32_e32 v79, v81
	s_nop 0
	s_waitcnt lgkmcnt(6)
	v_mfma_f32_32x32x16_bf16 v[50:65], v[66:69], v[82:85], v[50:65]
	ds_read_b64_tr_b16 v[82:83], v153 offset:0x8200
	ds_read_b64_tr_b16 v[84:85], v153 offset:0x8a00
	s_waitcnt lgkmcnt(6)
	v_mfma_f32_32x32x16_bf16 v[50:65], v[70:73], v[86:89], v[50:65]
	ds_read_b64_tr_b16 v[86:87], v153 offset:0x9200
	ds_read_b64_tr_b16 v[88:89], v153 offset:0x9a00
	s_waitcnt lgkmcnt(6)
	v_mfma_f32_32x32x16_bf16 v[50:65], v[74:77], v[90:93], v[50:65]
	ds_read_b64_tr_b16 v[90:91], v153 offset:0xa200
	ds_read_b64_tr_b16 v[92:93], v153 offset:0xaa00
	s_waitcnt lgkmcnt(6)
	v_mfma_f32_32x32x16_bf16 v[50:65], v[78:81], v[94:97], v[50:65]
	s_andn2_b64 vcc, exec, s[72:73]
	s_cbranch_vccnz .Lattn_sw2
	s_waitcnt vmcnt(1)
	ds_write_b128 v173, v[118:121]
	s_waitcnt vmcnt(0)
	ds_write_b128 v175, v[126:129]
	v_and_b32_e32 v252, 48, v209
	v_or_b32_e32 v252, s101, v252
	v_add_co_u32_e32 v250, vcc, 0xfff0f800, v200
	s_nop 1
	v_addc_co_u32_e32 v251, vcc, -1, v201, vcc
	v_xor_b32_e32 v250, v250, v252
	s_add_u32 m0, s100, 0
	s_nop 0
	global_load_lds_dwordx4 v[250:251], off
	v_add_co_u32_e32 v250, vcc, 0xfff3f800, v200
	s_nop 1
	v_addc_co_u32_e32 v251, vcc, -1, v201, vcc
	v_xor_b32_e32 v250, v250, v252
	s_add_u32 m0, s100, 0x2000
	s_nop 0
	global_load_lds_dwordx4 v[250:251], off
.Lattn_sw2:
	s_add_i32 s8, s99, 5
	s_cmp_lt_u32 s8, s79
	s_cselect_b64 s[38:39], -1, 0
	s_cmp_ge_u32 s8, s79
	s_cbranch_scc1 .Lattn_sl2
	v_and_b32_e32 v252, 48, v209
	v_or_b32_e32 v252, s101, v252
	v_add_co_u32_e32 v250, vcc, 0xfff6f800, v200
	s_nop 1
	v_addc_co_u32_e32 v251, vcc, -1, v201, vcc
	v_xor_b32_e32 v250, v250, v252
	s_add_u32 m0, s100, 0x4000
	s_nop 0
	global_load_lds_dwordx4 v[250:251], off
	v_add_co_u32_e32 v250, vcc, 0xfff9f800, v200
	s_nop 1
	v_addc_co_u32_e32 v251, vcc, -1, v201, vcc
	v_xor_b32_e32 v250, v250, v252
	s_add_u32 m0, s100, 0x6000
	s_nop 0
	global_load_lds_dwordx4 v[250:251], off
	v_add_co_u32_e32 v250, vcc, 0xfff70000, v200
	s_nop 1
	v_addc_co_u32_e32 v251, vcc, -1, v201, vcc
	global_load_dwordx4 v[118:121], v[250:251], off
	v_add_co_u32_e32 v250, vcc, 0xfffa0000, v200
	s_nop 1
	v_addc_co_u32_e32 v251, vcc, -1, v201, vcc
	global_load_dwordx4 v[126:129], v[250:251], off

.LBB0_206:
	v_cndmask_b32_e64 v233, v237, v233, s[8:9]
	v_mul_f32_e32 v206, 0xbe38aa3b, v233
	v_fmamk_f32 v82, v82, 0x3e38aa3b, v206
	v_fmamk_f32 v83, v83, 0x3e38aa3b, v206
	v_fmamk_f32 v84, v84, 0x3e38aa3b, v206
	v_fmamk_f32 v85, v85, 0x3e38aa3b, v206
	v_fmamk_f32 v86, v86, 0x3e38aa3b, v206
	v_fmamk_f32 v87, v87, 0x3e38aa3b, v206
	v_fmamk_f32 v88, v88, 0x3e38aa3b, v206
	v_fmamk_f32 v89, v89, 0x3e38aa3b, v206
	v_fmamk_f32 v90, v90, 0x3e38aa3b, v206
	v_fmamk_f32 v91, v91, 0x3e38aa3b, v206
	v_fmamk_f32 v92, v92, 0x3e38aa3b, v206
	v_fmamk_f32 v93, v93, 0x3e38aa3b, v206
	v_fmamk_f32 v94, v94, 0x3e38aa3b, v206
	v_fmamk_f32 v95, v95, 0x3e38aa3b, v206
	v_fmamk_f32 v96, v96, 0x3e38aa3b, v206
	v_fmamk_f32 v97, v97, 0x3e38aa3b, v206
	v_fmamk_f32 v66, v66, 0x3e38aa3b, v206
	v_fmamk_f32 v67, v67, 0x3e38aa3b, v206
	v_fmamk_f32 v68, v68, 0x3e38aa3b, v206
	v_fmamk_f32 v69, v69, 0x3e38aa3b, v206
	v_fmamk_f32 v70, v70, 0x3e38aa3b, v206
	v_fmamk_f32 v71, v71, 0x3e38aa3b, v206
	v_fmamk_f32 v72, v72, 0x3e38aa3b, v206
	v_fmamk_f32 v73, v73, 0x3e38aa3b, v206
	v_fmamk_f32 v74, v74, 0x3e38aa3b, v206
	v_fmamk_f32 v75, v75, 0x3e38aa3b, v206
	v_fmamk_f32 v76, v76, 0x3e38aa3b, v206
	v_fmamk_f32 v77, v77, 0x3e38aa3b, v206
	v_fmamk_f32 v78, v78, 0x3e38aa3b, v206
	v_fmamk_f32 v79, v79, 0x3e38aa3b, v206
	v_fmamk_f32 v80, v80, 0x3e38aa3b, v206
	v_fmac_f32_e32 v206, 0x3e38aa3b, v81
	v_exp_f32_e32 v81, v82
	v_exp_f32_e32 v82, v83
	v_exp_f32_e32 v83, v84
	v_exp_f32_e32 v84, v85
	v_exp_f32_e32 v85, v86
	v_exp_f32_e32 v86, v87
	v_exp_f32_e32 v87, v88
	v_exp_f32_e32 v88, v89
	v_exp_f32_e32 v89, v90
	v_exp_f32_e32 v90, v91
	v_exp_f32_e32 v91, v92
	v_exp_f32_e32 v92, v93
	v_exp_f32_e32 v93, v94
	v_exp_f32_e32 v94, v95
	v_exp_f32_e32 v95, v96
	v_exp_f32_e32 v96, v97
	v_add_f32_e32 v97, v234, v235
	v_fmac_f32_e32 v97, v232, v1
	v_exp_f32_e32 v1, v66
	v_add_f32_e32 v66, 0, v81
	v_add_f32_e32 v66, v82, v66
	v_add_f32_e32 v66, v83, v66
	v_add_f32_e32 v66, v84, v66
	v_add_f32_e32 v66, v85, v66
	v_add_f32_e32 v66, v86, v66
	v_add_f32_e32 v66, v87, v66
	v_add_f32_e32 v66, v88, v66
	v_add_f32_e32 v66, v89, v66
	v_add_f32_e32 v66, v90, v66
	v_add_f32_e32 v66, v91, v66
	v_add_f32_e32 v66, v92, v66
	v_add_f32_e32 v66, v93, v66
	v_exp_f32_e32 v212, v67
	v_add_f32_e32 v66, v94, v66
	v_exp_f32_e32 v213, v68
	v_add_f32_e32 v66, v95, v66
	v_exp_f32_e32 v214, v69
	v_add_f32_e32 v66, v96, v66
	v_exp_f32_e32 v215, v70
	v_add_f32_e32 v66, v1, v66
	v_exp_f32_e32 v234, v71
	v_add_f32_e32 v66, v212, v66
	v_exp_f32_e32 v235, v72
	v_add_f32_e32 v66, v213, v66
	v_exp_f32_e32 v237, v73
	v_add_f32_e32 v66, v214, v66
	v_exp_f32_e32 v238, v74
	v_add_f32_e32 v66, v215, v66
	v_exp_f32_e32 v239, v75
	v_add_f32_e32 v66, v234, v66
	v_exp_f32_e32 v240, v76
	v_add_f32_e32 v66, v235, v66
	v_exp_f32_e32 v241, v77
	v_add_f32_e32 v66, v237, v66
	v_exp_f32_e32 v242, v78
	v_add_f32_e32 v66, v238, v66
	v_exp_f32_e32 v243, v79
	v_add_f32_e32 v66, v239, v66
	v_exp_f32_e32 v244, v80
	v_add_f32_e32 v66, v240, v66
	v_exp_f32_e32 v206, v206
	v_add_f32_e32 v66, v241, v66
	v_add_f32_e32 v66, v242, v66
	v_add_f32_e32 v66, v243, v66
	v_add_f32_e32 v66, v244, v66
	v_add_f32_e32 v66, v206, v66
	v_mov_b32_e32 v67, v66
	s_nop 1
	v_permlane32_swap_b32_e32 v66, v67
	v_add_f32_e32 v232, v66, v67
	v_fmac_f32_e32 v232, v97, v236
	v_cvt_pk_bf16_f32 v66, v81, v82
	v_cvt_pk_bf16_f32 v67, v83, v84
	v_cvt_pk_bf16_f32 v68, v85, v86
	v_cvt_pk_bf16_f32 v69, v87, v88
	v_cvt_pk_bf16_f32 v70, v89, v90
	v_cvt_pk_bf16_f32 v71, v91, v92
	v_cvt_pk_bf16_f32 v72, v93, v94
	v_cvt_pk_bf16_f32 v73, v95, v96
	ds_read_b64_tr_b16 v[82:83], v153 offset:0xc000
	ds_read_b64_tr_b16 v[84:85], v153 offset:0xc800
	ds_read_b64_tr_b16 v[86:87], v153 offset:0xd000
	ds_read_b64_tr_b16 v[88:89], v153 offset:0xd800
	ds_read_b64_tr_b16 v[90:91], v153 offset:0xe000
	ds_read_b64_tr_b16 v[92:93], v153 offset:0xe800
	ds_read_b64_tr_b16 v[94:95], v153 offset:0xf000
	ds_read_b64_tr_b16 v[96:97], v153 offset:0xf800
	v_cvt_pk_bf16_f32 v74, v1, v212
	v_cvt_pk_bf16_f32 v75, v213, v214
	v_cvt_pk_bf16_f32 v76, v215, v234
	v_cvt_pk_bf16_f32 v77, v235, v237
	v_cvt_pk_bf16_f32 v78, v238, v239
	v_cvt_pk_bf16_f32 v79, v240, v241
	v_cvt_pk_bf16_f32 v80, v242, v243
	v_cvt_pk_bf16_f32 v81, v244, v206
	s_nop 0
	v_permlane32_swap_b32_e32 v66, v68
	v_permlane32_swap_b32_e32 v67, v69
	v_permlane32_swap_b32_e32 v70, v72
	v_permlane32_swap_b32_e32 v71, v73
	v_permlane32_swap_b32_e32 v74, v76
	v_permlane32_swap_b32_e32 v75, v77
	v_permlane32_swap_b32_e32 v78, v80
	v_permlane32_swap_b32_e32 v79, v81
	s_nop 0
	s_waitcnt lgkmcnt(6)
	v_mfma_f32_32x32x16_bf16 v[50:65], v[66:69], v[82:85], v[50:65]
	ds_read_b64_tr_b16 v[82:83], v153 offset:0xc200
	ds_read_b64_tr_b16 v[84:85], v153 offset:0xca00
	s_waitcnt lgkmcnt(6)
	v_mfma_f32_32x32x16_bf16 v[50:65], v[70:73], v[86:89], v[50:65]
	ds_read_b64_tr_b16 v[86:87], v153 offset:0xd200
	ds_read_b64_tr_b16 v[88:89], v153 offset:0xda00
	s_waitcnt lgkmcnt(6)
	v_mfma_f32_32x32x16_bf16 v[50:65], v[74:77], v[90:93], v[50:65]
	ds_read_b64_tr_b16 v[90:91], v153 offset:0xe200
	ds_read_b64_tr_b16 v[92:93], v153 offset:0xea00
	s_waitcnt lgkmcnt(6)
	v_mfma_f32_32x32x16_bf16 v[50:65], v[78:81], v[94:97], v[50:65]
	s_andn2_b64 vcc, exec, s[38:39]
	s_cbranch_vccnz .Lattn_sw3
	s_waitcnt vmcnt(1)
	ds_write_b128 v229, v[118:121]
	s_waitcnt vmcnt(0)
	ds_write_b128 v230, v[126:129]
.Lattn_sw3:
	s_add_i32 s8, s99, 6
	s_cmp_gt_u32 s8, s33
	s_cbranch_scc1 .Lattn_sl3
	v_add_co_u32_e32 v250, vcc, 0xfffd0000, v200
	s_nop 1
	v_addc_co_u32_e32 v251, vcc, -1, v201, vcc
	global_load_dwordx4 v[118:121], v[250:251], off
	global_load_dwordx4 v[126:129], v[200:201], off

	.amdhsa_kernel _Z14fwd_megakernel6Params
		.amdhsa_group_segment_fixed_size 0
		.amdhsa_private_segment_fixed_size 0
		.amdhsa_kernarg_size 504
		.amdhsa_user_sgpr_count 2
		.amdhsa_user_sgpr_dispatch_ptr 0
		.amdhsa_user_sgpr_queue_ptr 0
		.amdhsa_user_sgpr_kernarg_segment_ptr 1
		.amdhsa_user_sgpr_dispatch_id 0
		.amdhsa_user_sgpr_kernarg_preload_length 0
		.amdhsa_user_sgpr_kernarg_preload_offset 0
		.amdhsa_user_sgpr_private_segment_size 0
		.amdhsa_uses_dynamic_stack 0
		.amdhsa_enable_private_segment 0
		.amdhsa_system_sgpr_workgroup_id_x 1
		.amdhsa_system_sgpr_workgroup_id_y 0
		.amdhsa_system_sgpr_workgroup_id_z 0
		.amdhsa_system_sgpr_workgroup_info 0
		.amdhsa_system_vgpr_workitem_id 2
		.amdhsa_next_free_vgpr 256
		.amdhsa_next_free_sgpr 102
		.amdhsa_accum_offset 256
		.amdhsa_reserve_vcc 1
		.amdhsa_float_round_mode_32 0
		.amdhsa_float_round_mode_16_64 0
		.amdhsa_float_denorm_mode_32 3
		.amdhsa_float_denorm_mode_16_64 3
		.amdhsa_dx10_clamp 1
		.amdhsa_ieee_mode 1
		.amdhsa_fp16_overflow 0
		.amdhsa_tg_split 0
		.amdhsa_exception_fp_ieee_invalid_op 0
		.amdhsa_exception_fp_denorm_src 0
		.amdhsa_exception_fp_ieee_div_zero 0
		.amdhsa_exception_fp_ieee_overflow 0
		.amdhsa_exception_fp_ieee_underflow 0
		.amdhsa_exception_fp_ieee_inexact 0
		.amdhsa_exception_int_div_zero 0
	.end_amdhsa_kernel

amdhsa.kernels:
  - .agpr_count:     0
    .args:
      - .offset:         0
        .size:           248
        .value_kind:     by_value
      - .offset:         248
        .size:           4
        .value_kind:     hidden_block_count_x
      - .offset:         252
        .size:           4
        .value_kind:     hidden_block_count_y
      - .offset:         256
        .size:           4
        .value_kind:     hidden_block_count_z
      - .offset:         260
        .size:           2
        .value_kind:     hidden_group_size_x
      - .offset:         262
        .size:           2
        .value_kind:     hidden_group_size_y
      - .offset:         264
        .size:           2
        .value_kind:     hidden_group_size_z
      - .offset:         266
        .size:           2
        .value_kind:     hidden_remainder_x
      - .offset:         268
        .size:           2
        .value_kind:     hidden_remainder_y
      - .offset:         270
        .size:           2
        .value_kind:     hidden_remainder_z
      - .offset:         288
        .size:           8
        .value_kind:     hidden_global_offset_x
      - .offset:         296
        .size:           8
        .value_kind:     hidden_global_offset_y
      - .offset:         304
        .size:           8
        .value_kind:     hidden_global_offset_z
      - .offset:         312
        .size:           2
        .value_kind:     hidden_grid_dims
      - .offset:         336
        .size:           8
        .value_kind:     hidden_multigrid_sync_arg
      - .offset:         368
        .size:           4
        .value_kind:     hidden_dynamic_lds_size
    .group_segment_fixed_size: 0
    .kernarg_segment_align: 8
    .kernarg_segment_size: 504
    .language:       OpenCL C
    .language_version:
      - 2
      - 0
    .max_flat_workgroup_size: 512
    .name:           _Z14fwd_megakernel6Params
    .private_segment_fixed_size: 0
    .sgpr_count:     108
    .sgpr_spill_count: 88
    .symbol:         _Z14fwd_megakernel6Params.kd
    .uniform_work_group_size: 1
    .uses_dynamic_stack: false
    .vgpr_count:     256
    .vgpr_spill_count: 0
    .wavefront_size: 64
  - .agpr_count:     0
    .args:
      - .address_space:  global
        .offset:         0
        .size:           8
        .value_kind:     global_buffer
      - .offset:         8
        .size:           4
        .value_kind:     by_value
      - .address_space:  global
        .offset:         16
        .size:           8
        .value_kind:     global_buffer
      - .offset:         24
        .size:           4
        .value_kind:     hidden_block_count_x
      - .offset:         28
        .size:           4
        .value_kind:     hidden_block_count_y
      - .offset:         32
        .size:           4
        .value_kind:     hidden_block_count_z
      - .offset:         36
        .size:           2
        .value_kind:     hidden_group_size_x
      - .offset:         38
        .size:           2
        .value_kind:     hidden_group_size_y
      - .offset:         40
        .size:           2
        .value_kind:     hidden_group_size_z
      - .offset:         42
        .size:           2
        .value_kind:     hidden_remainder_x
      - .offset:         44
        .size:           2
        .value_kind:     hidden_remainder_y
      - .offset:         46
        .size:           2
        .value_kind:     hidden_remainder_z
      - .offset:         64
        .size:           8
        .value_kind:     hidden_global_offset_x
      - .offset:         72
        .size:           8
        .value_kind:     hidden_global_offset_y
      - .offset:         80
        .size:           8
        .value_kind:     hidden_global_offset_z
      - .offset:         88
        .size:           2
        .value_kind:     hidden_grid_dims
    .group_segment_fixed_size: 0
    .kernarg_segment_align: 8
    .kernarg_segment_size: 280
    .language:       OpenCL C
    .language_version:
      - 2
      - 0
    .max_flat_workgroup_size: 1024
    .name:           _Z8dbg_copyPKtiPf
    .private_segment_fixed_size: 0
    .sgpr_count:     34
    .sgpr_spill_count: 0
    .symbol:         _Z8dbg_copyPKtiPf.kd
    .uniform_work_group_size: 1
    .uses_dynamic_stack: false
    .vgpr_count:     27
    .vgpr_spill_count: 0
    .wavefront_size: 64
  - .agpr_count:     0
    .args:
      - .address_space:  global
        .offset:         0
        .size:           8
        .value_kind:     global_buffer
      - .address_space:  global
        .offset:         8
        .size:           8
        .value_kind:     global_buffer
      - .offset:         16
        .size:           4
        .value_kind:     hidden_block_count_x
      - .offset:         20
        .size:           4
        .value_kind:     hidden_block_count_y
      - .offset:         24
        .size:           4
        .value_kind:     hidden_block_count_z
      - .offset:         28
        .size:           2
        .value_kind:     hidden_group_size_x
      - .offset:         30
        .size:           2
        .value_kind:     hidden_group_size_y
      - .offset:         32
        .size:           2
        .value_kind:     hidden_group_size_z
      - .offset:         34
        .size:           2
        .value_kind:     hidden_remainder_x
      - .offset:         36
        .size:           2
        .value_kind:     hidden_remainder_y
      - .offset:         38
        .size:           2
        .value_kind:     hidden_remainder_z
      - .offset:         56
        .size:           8
        .value_kind:     hidden_global_offset_x
      - .offset:         64
        .size:           8
        .value_kind:     hidden_global_offset_y
      - .offset:         72
        .size:           8
        .value_kind:     hidden_global_offset_z
      - .offset:         80
        .size:           2
        .value_kind:     hidden_grid_dims
    .group_segment_fixed_size: 0
    .kernarg_segment_align: 8
    .kernarg_segment_size: 272
    .language:       OpenCL C
    .language_version:
      - 2
      - 0
    .max_flat_workgroup_size: 1024
    .name:           _Z9dbg_copyfPKfPf
    .private_segment_fixed_size: 0
    .sgpr_count:     17
    .sgpr_spill_count: 0
    .symbol:         _Z9dbg_copyfPKfPf.kd
    .uniform_work_group_size: 1
    .uses_dynamic_stack: false
    .vgpr_count:     6
    .vgpr_spill_count: 0
    .wavefront_size: 64
  - .agpr_count:     0
    .args:
      - .address_space:  global
        .offset:         0
        .size:           8
        .value_kind:     global_buffer
      - .offset:         8
        .size:           4
        .value_kind:     by_value
      - .address_space:  global
        .offset:         16
        .size:           8
        .value_kind:     global_buffer
      - .offset:         24
        .size:           4
        .value_kind:     by_value
      - .address_space:  global
        .offset:         32
        .size:           8
        .value_kind:     global_buffer
      - .address_space:  global
        .offset:         40
        .size:           8
        .value_kind:     global_buffer
      - .offset:         48
        .size:           4
        .value_kind:     hidden_block_count_x
      - .offset:         52
        .size:           4
        .value_kind:     hidden_block_count_y
      - .offset:         56
        .size:           4
        .value_kind:     hidden_block_count_z
      - .offset:         60
        .size:           2
        .value_kind:     hidden_group_size_x
      - .offset:         62
        .size:           2
        .value_kind:     hidden_group_size_y
      - .offset:         64
        .size:           2
        .value_kind:     hidden_group_size_z
      - .offset:         66
        .size:           2
        .value_kind:     hidden_remainder_x
      - .offset:         68
        .size:           2
        .value_kind:     hidden_remainder_y
      - .offset:         70
        .size:           2
        .value_kind:     hidden_remainder_z
      - .offset:         88
        .size:           8
        .value_kind:     hidden_global_offset_x
      - .offset:         96
        .size:           8
        .value_kind:     hidden_global_offset_y
      - .offset:         104
        .size:           8
        .value_kind:     hidden_global_offset_z
      - .offset:         112
        .size:           2
        .value_kind:     hidden_grid_dims
    .group_segment_fixed_size: 0
    .kernarg_segment_align: 8
    .kernarg_segment_size: 304
    .language:       OpenCL C
    .language_version:
      - 2
      - 0
    .max_flat_workgroup_size: 1024
    .name:           _Z9dbg_copy2PKtiS0_iPKfPf
    .private_segment_fixed_size: 0
    .sgpr_count:     26
    .sgpr_spill_count: 0
    .symbol:         _Z9dbg_copy2PKtiS0_iPKfPf.kd
    .uniform_work_group_size: 1
    .uses_dynamic_stack: false
    .vgpr_count:     15
    .vgpr_spill_count: 0
    .wavefront_size: 64
